# move the late-needed weight transposes (WOUT,WGU,WD,WPG,WPP) and p->bf16 out of the HBM-bound P0 into P2 (after each workgroup's 1st/2nd queue item), where HBM is idle
# speedup vs baseline: 1.0055x; 1.0042x over previous
_Z8skel_fwd4Args:
	s_mov_b32 s99, 0
	s_load_dwordx8 s[68:75], s[0:1], 0x80
	s_load_dword s3, s[0:1], 0xb0
	s_load_dwordx2 s[76:77], s[0:1], 0xa0
	s_load_dword s4, s[0:1], 0xa8
	v_mov_b32_e32 v3, 0
	v_and_b32_e32 v1, 0x3ff, v0
	s_add_u32 s6, s0, 0xb0
	v_readfirstlane_b32 s33, v1
	v_mbcnt_lo_u32_b32 v3, -1, v3
	s_addc_u32 s7, s1, 0
	s_andn2_b32 s33, s33, 63
	v_mbcnt_hi_u32_b32 v3, -1, v3
	v_add_u32_e32 v3, s33, v3
	s_waitcnt lgkmcnt(0)
	v_writelane_b32 v255, s4, 0
	v_writelane_b32 v255, s0, 32
	v_writelane_b32 v255, s1, 33
	v_mov_b32_e32 v2, 0
	s_nop 0
	v_cmp_eq_u32_e32 vcc, 0, v3
	s_and_saveexec_b64 s[4:5], vcc
	s_cbranch_execz .LBB0_3
	s_add_i32 s10, 0, 0x25fd0
	v_mov_b32_e32 v3, s10
	s_add_i32 s10, 0, 0x25fd4
	s_mov_b64 s[8:9], exec
	ds_write_b32 v3, v2
	v_mov_b32_e32 v3, s10
	ds_write_b32 v3, v2
	v_mbcnt_lo_u32_b32 v2, s8, 0
	v_mbcnt_hi_u32_b32 v2, s9, v2
	v_cmp_eq_u32_e32 vcc, 0, v2
	s_getreg_b32 s10, hwreg(HW_REG_XCC_ID, 0, 4)
	s_and_b64 s[12:13], exec, vcc
	s_mov_b64 exec, s[12:13]
	s_cbranch_execz .LBB0_3
	s_and_b32 s98, s10, 15
	s_add_i32 s98, s98, 1
	s_lshl_b32 s100, s2, 2
	s_add_i32 s100, s100, 0xe000
	v_mov_b32_e32 v4, s100
	v_mov_b32_e32 v5, s98
	global_atomic_add v4, v5, s[76:77]
	s_lshl_b32 s10, s10, 8
	s_and_b32 s10, s10, 0xf00
	s_add_u32 s10, s76, s10
	s_addc_u32 s11, s77, 0
	s_bcnt1_i32_b64 s8, s[8:9]
	v_mov_b32_e32 v2, 0x8000
	v_mov_b32_e32 v3, s8
	global_atomic_add v2, v3, s[10:11] offset:1024

.Lp0_entry:
	s_movk_i32 s101, 0xcff
	s_bitcmp1_b32 s99, 2
	s_cbranch_scc0 .Lp0_b1
	s_movk_i32 s101, 0x21ff
.Lp0_b1:
	v_mov_b32_e32 v0, 0
	s_lshl_b32 s1, s2, 3
	v_mbcnt_lo_u32_b32 v0, -1, v0
	v_mbcnt_hi_u32_b32 v0, -1, v0
	v_add_u32_e32 v192, s33, v0
	s_lshl_b32 s78, s3, 3
	v_readfirstlane_b32 s0, v192
	s_ashr_i32 s0, s0, 6
	v_and_b32_e32 v193, 63, v192
	s_add_i32 s20, s0, s1
	v_mov_b32_e32 v1, 0
	s_cmp_gt_i32 s20, s101
	v_lshlrev_b32_e32 v16, 3, v193
	s_cbranch_scc1 .LBB0_53
	s_lshl_b32 s0, s0, 14
	v_lshrrev_b32_e32 v17, 5, v193
	v_and_b32_e32 v34, 31, v192
	s_add_i32 s0, s0, 0
	v_lshlrev_b32_e32 v0, 2, v34
	v_mul_u32_u24_e32 v4, 0x84, v17
	v_add3_u32 v130, s0, v0, v4
	v_and_b32_e32 v4, 56, v16
	v_mul_u32_u24_e32 v6, 0x84, v4
	v_lshlrev_b32_e32 v4, 1, v4
	v_mov_b32_e32 v5, v1
	v_lshl_add_u64 v[32:33], s[76:77], 0, v[4:5]
	s_mov_b64 s[8:9], 0x1000000
	s_mov_b64 s[4:5], 0x2300000
	s_cmp_lg_u64 s[68:69], 0
	s_mov_b64 s[6:7], 0x2100000
	v_lshl_add_u64 v[14:15], v[32:33], 0, s[8:9]
	s_mov_b64 s[8:9], 0xe00000
	v_lshrrev_b32_e32 v131, 3, v193
	v_lshl_add_u64 v[4:5], v[32:33], 0, s[4:5]
	s_cselect_b64 s[4:5], -1, 0
	v_lshl_add_u64 v[8:9], v[32:33], 0, s[6:7]
	s_mov_b64 s[6:7], 0x1b00000
	s_waitcnt lgkmcnt(0)
	s_cmp_lg_u64 s[60:61], 0
	v_lshl_add_u64 v[20:21], v[32:33], 0, s[8:9]
	s_mov_b64 s[8:9], 0xd00000
	v_lshlrev_b32_e32 v7, 2, v131
	v_lshl_add_u64 v[12:13], v[32:33], 0, s[6:7]
	s_cselect_b64 s[6:7], -1, 0
	v_lshl_add_u64 v[24:25], v[32:33], 0, s[8:9]
	s_mov_b64 s[8:9], 0xc00000
	s_cmp_lg_u64 s[40:41], 0
	s_mov_b64 s[10:11], 0x100000
	s_mov_b32 s1, 0
	v_lshl_add_u64 v[2:3], s[72:73], 0, v[0:1]
	v_add3_u32 v132, s0, v6, v7
	v_or_b32_e32 v133, 8, v131
	v_or_b32_e32 v134, 16, v131
	v_or_b32_e32 v135, 24, v131
	v_lshl_add_u64 v[6:7], s[70:71], 0, v[0:1]
	v_lshl_add_u64 v[10:11], s[66:67], 0, v[0:1]
	v_lshl_add_u64 v[18:19], s[58:59], 0, v[0:1]
	v_lshl_add_u64 v[22:23], s[56:57], 0, v[0:1]
	v_lshl_add_u64 v[26:27], s[54:55], 0, v[0:1]
	v_lshl_add_u64 v[28:29], v[32:33], 0, s[8:9]
	v_lshl_add_u64 v[30:31], s[42:43], 0, v[0:1]
	s_cselect_b64 s[8:9], -1, 0
	v_lshl_add_u64 v[32:33], v[32:33], 0, s[10:11]
	s_lshl_b32 s12, s20, 5
	s_lshl_b32 s13, s78, 5
	s_lshl_b32 s14, s20, 6
	s_lshl_b32 s15, s78, 6
	s_lshl_b32 s16, s20, 1
	s_lshl_b32 s17, s78, 1
	v_lshlrev_b32_e32 v0, 2, v34
	s_movk_i32 s18, 0x2c00
	s_movk_i32 s19, 0x5820
	v_add_u32_e32 v136, 0x400, v130
	v_add_u32_e32 v137, 0x800, v130
	v_add_u32_e32 v138, 0xc00, v130
	v_add_u32_e32 v139, 0x1000, v130
	v_add_u32_e32 v140, 0x1400, v130
	v_add_u32_e32 v141, 0x1800, v130
	v_add_u32_e32 v142, 0x1c00, v130
	s_mov_b32 s21, s20
	s_bitcmp1_b32 s99, 2
	s_cbranch_scc0 .Lp0_st
.Lp0_adv:
	s_cmpk_gt_i32 s21, 0xcff
	s_cbranch_scc1 .Lp0_st2
	s_add_i32 s21, s21, s78
	s_add_i32 s12, s12, s13
	s_add_i32 s14, s14, s15
	s_add_i32 s16, s16, s17
	s_branch .Lp0_adv
.Lp0_st2:
	s_cmp_gt_i32 s21, s101
	s_cbranch_scc1 .LBB0_53
.Lp0_st:
	s_branch .LBB0_20

.LBB0_19:
	s_add_i32 s21, s21, s78
	s_add_i32 s12, s12, s13
	s_add_i32 s14, s14, s15
	s_add_i32 s16, s16, s17
	s_cmp_gt_i32 s21, s101
	s_cbranch_scc1 .LBB0_53

.LBB0_53:
	s_bitcmp1_b32 s99, 2
	s_cbranch_scc1 .LBB0_65
	s_movk_i32 s0, 0x800
	v_cmp_gt_i32_e32 vcc, s0, v192
	s_waitcnt lgkmcnt(0)
	s_barrier
	s_and_saveexec_b64 s[0:1], vcc
	s_cbranch_execz .LBB0_56
	v_lshlrev_b32_e32 v4, 2, v192
	s_mov_b64 s[4:5], 0
	s_movk_i32 s6, 0x5820
	v_mov_b64_e32 v[0:1], s[42:43]
	v_mov_b32_e32 v3, 0
	s_mov_b32 s7, 0x1ffffc
	s_movk_i32 s8, 0x5ff
	v_mov_b32_e32 v5, v192

.LBB0_65:
	s_bitcmp1_b32 s99, 2
	s_cbranch_scc0 .LBB0_73
	v_lshl_add_u32 v0, s2, 9, v192
	s_mov_b32 s0, 0x100000
	v_cmp_gt_i32_e32 vcc, s0, v0
	s_and_saveexec_b64 s[4:5], vcc
	s_cbranch_execz .LBB0_73
	s_lshl_b32 s6, s3, 9
	v_cvt_f32_u32_e32 v1, s6
	v_add_u32_e32 v2, s6, v0
	v_mov_b32_e32 v3, s6
	s_sub_i32 s7, 0, s6
	v_rcp_iflag_f32_e32 v1, v1
	v_cmp_gt_i32_e32 vcc, s0, v2
	v_max_i32_e32 v4, 0x100000, v2
	v_mul_f32_e32 v1, 0x4f7ffffe, v1
	v_cvt_u32_f32_e32 v1, v1
	v_addc_co_u32_e64 v2, s[0:1], v0, v3, vcc
	v_sub_u32_e32 v2, v4, v2
	v_mul_lo_u32 v3, s7, v1
	v_mul_hi_u32 v3, v1, v3
	v_add_u32_e32 v1, v1, v3
	v_mul_hi_u32 v1, v2, v1
	v_mul_lo_u32 v3, v1, s6
	v_sub_u32_e32 v2, v2, v3
	v_add_u32_e32 v4, 1, v1
	v_cmp_le_u32_e64 s[0:1], s6, v2
	v_subrev_u32_e32 v3, s6, v2
	s_nop 0
	v_cndmask_b32_e64 v1, v1, v4, s[0:1]
	v_cndmask_b32_e64 v2, v2, v3, s[0:1]
	v_add_u32_e32 v3, 1, v1
	v_cmp_le_u32_e64 s[0:1], s6, v2
	s_nop 1
	v_cndmask_b32_e64 v1, v1, v3, s[0:1]
	v_addc_co_u32_e32 v6, vcc, 0, v1, vcc
	v_and_b32_e32 v1, 3, v6
	v_cmp_ne_u32_e32 vcc, 3, v1
	s_and_saveexec_b64 s[0:1], vcc
	s_cbranch_execz .LBB0_70
	v_add_u32_e32 v1, 1, v6
	v_and_b32_e32 v7, 3, v1
	v_ashrrev_i32_e32 v1, 31, v0
	v_lshlrev_b64 v[4:5], 5, v[0:1]
	v_lshl_add_u64 v[2:3], v[0:1], 4, s[76:77]
	s_mov_b64 s[8:9], 0x6c00000
	s_ashr_i32 s7, s6, 31
	v_lshl_add_u64 v[4:5], s[38:39], 0, v[4:5]
	v_lshl_add_u64 v[2:3], v[2:3], 0, s[8:9]
	s_lshl_b64 s[8:9], s[6:7], 4
	v_lshl_add_u64 v[4:5], v[4:5], 0, 16
	s_lshl_b64 s[12:13], s[6:7], 5
	s_mov_b64 s[10:11], 0

.LBB0_73:
	s_or_b64 exec, exec, s[4:5]
	s_bitcmp1_b32 s99, 2
	s_cbranch_scc0 .Lp0_noret
	s_waitcnt lgkmcnt(0)
	s_barrier
	v_readlane_b32 s27, v255, 0
	v_readlane_b32 s54, v255, 1
	v_readlane_b32 s55, v255, 2
	s_add_u32 s40, s76, 0x7c00000
	s_addc_u32 s41, s77, 0
	s_bitcmp1_b32 s99, 3
	s_cbranch_scc1 .Lp0_retx
	s_andn2_b32 s99, s99, 12
	s_branch .Lp2_prologue
.Lp0_retx:
	s_andn2_b32 s99, s99, 12
	s_branch .Lp0b_ret_exit
.Lp0_noret:
	v_mov_b32_e32 v0, 0
	s_nop 0
	v_mbcnt_lo_u32_b32 v0, -1, v0
	v_mbcnt_hi_u32_b32 v0, -1, v0
	v_add_u32_e32 v0, s33, v0
	s_waitcnt vmcnt(0)
	s_nop 0
	v_cmp_eq_u32_e32 vcc, 0, v0
	s_barrier
	s_and_saveexec_b64 s[0:1], vcc
	s_cbranch_execz .LBB0_125
	s_add_i32 s5, 0, 0x25fd0
	v_mov_b32_e32 v0, s5
	s_getreg_b32 s4, hwreg(HW_REG_XCC_ID, 0, 4)
	s_waitcnt vmcnt(0) expcnt(0) lgkmcnt(0)
	ds_read_b32 v2, v0
	s_add_i32 s5, 0, 0x25fd4
	v_mov_b32_e32 v0, s5
	ds_read_b32 v0, v0
	s_and_b32 s58, s4, 15
	s_waitcnt lgkmcnt(1)
	v_cmp_ne_u32_e32 vcc, 0, v2
	s_cbranch_vccnz .LBB0_89
	s_add_u32 s4, s76, 0x8200
	s_addc_u32 s5, s77, 0
	s_add_u32 s6, s76, 0x8400
	s_addc_u32 s7, s77, 0
	s_add_u32 s8, s76, 0x8500
	s_addc_u32 s9, s77, 0
	s_add_u32 s10, s76, 0x8600
	s_addc_u32 s11, s77, 0
	s_add_u32 s12, s76, 0x8700
	s_addc_u32 s13, s77, 0
	s_add_u32 s14, s76, 0x8800
	s_addc_u32 s15, s77, 0
	s_add_u32 s16, s76, 0x8900
	s_addc_u32 s17, s77, 0
	s_add_u32 s18, s76, 0x8a00
	s_addc_u32 s19, s77, 0
	s_add_u32 s20, s76, 0x8b00
	s_addc_u32 s21, s77, 0
	s_add_u32 s22, s76, 0x8c00
	s_addc_u32 s23, s77, 0
	s_add_u32 s24, s76, 0x8d00
	s_addc_u32 s25, s77, 0
	s_add_u32 s26, s76, 0x8e00
	s_addc_u32 s27, s77, 0
	s_add_u32 s28, s76, 0x8f00
	s_addc_u32 s29, s77, 0
	s_add_u32 s30, s76, 0x9000
	s_addc_u32 s31, s77, 0
	s_add_u32 s38, s76, 0x9100
	s_addc_u32 s39, s77, 0
	s_add_u32 s40, s76, 0x9200
	s_addc_u32 s41, s77, 0
	s_add_u32 s42, s76, 0x9300
	s_addc_u32 s43, s77, 0
	s_mov_b32 s59, 1
	v_mov_b32_e32 v16, 0
	s_branch .LBB0_77

.LBB0_256:
	s_mov_b32 s98, 0
	s_cmp_lg_u32 s27, 2
	s_cselect_b64 s[0:1], -1, 0
	s_waitcnt lgkmcnt(0)
	s_xor_b64 s[54:55], s[4:5], -1
	s_and_b64 s[0:1], s[54:55], s[0:1]
	v_writelane_b32 v255, s54, 1
	s_and_b64 vcc, exec, s[0:1]
	s_nop 0
	v_writelane_b32 v255, s55, 2
	s_cbranch_vccnz .LBB0_590
.Lp2_prologue:
	s_add_u32 s0, s76, 0x7c01000
	v_writelane_b32 v255, s0, 3
	s_addc_u32 s0, s77, 0
	v_writelane_b32 v255, s0, 4
	s_add_u32 s0, s76, 0x7c01400
	s_addc_u32 s86, s77, 0
	s_add_u32 s87, s76, 0x7c01800
	s_addc_u32 s88, s77, 0
	s_add_u32 s84, s76, 0x1e400000
	s_addc_u32 s85, s77, 0
	s_add_u32 s48, s76, 0x1dc00000
	s_addc_u32 s49, s77, 0
	s_add_u32 s50, s76, 0x23c0000
	s_addc_u32 s51, s77, 0
	s_add_u32 s89, s76, 0x2600000
	s_addc_u32 s90, s77, 0
	s_add_u32 s52, s76, 0x7c00800
	v_writelane_b32 v255, s0, 5
	s_addc_u32 s53, s77, 0
	s_add_i32 s4, 0, 0x12200
	v_mov_b32_e32 v0, 0
	v_writelane_b32 v255, s4, 6
	s_add_i32 s4, 0, 0x15500
	v_writelane_b32 v255, s4, 7
	s_add_i32 s4, 0, 0x11100
	v_mbcnt_lo_u32_b32 v0, -1, v0
	v_writelane_b32 v255, s4, 8
	s_add_i32 s4, 0, 0x13300
	v_mbcnt_hi_u32_b32 v0, -1, v0
	v_writelane_b32 v255, s4, 9
	s_add_i32 s4, 0, 0x16600
	v_add_u32_e32 v0, s33, v0
	s_add_i32 s91, 0, 0x25fc0
	v_writelane_b32 v255, s4, 10
	s_mov_b32 s58, 0x652b82fe
	s_add_i32 s4, 0, 0x14c00
	s_mov_b32 s64, 0xfff50000
	v_mov_b32_e32 v99, 0
	s_mov_b32 s55, 0
	v_cmp_eq_u32_e64 s[0:1], 0, v0
	v_mov_b32_e32 v190, s91
	s_add_i32 s92, 0, 0x1d000
	s_movk_i32 s93, 0x6ff
	s_movk_i32 s94, 0x2c00
	s_mov_b32 s95, 0x58000
	s_add_i32 s96, 0, 0x1f600
	s_add_i32 s97, 0, 0x1f400
	s_add_i32 s42, 0, 0x10000
	s_add_i32 s43, 0, 0x14400
	s_add_i32 s82, 0, 0x18800
	s_movk_i32 s28, 0x90
	s_movk_i32 s45, 0x110
	v_mov_b32_e32 v191, 0x358637bd
	s_movk_i32 s62, 0x7fff
	s_mov_b32 s63, 0x7c00000
	s_mov_b32 s44, 0x7c03000
	s_mov_b32 s59, 0x3ff71547
	s_mov_b64 s[60:61], 0x160000
	s_mov_b32 s38, 0x3f803f80
	s_mov_b64 s[80:81], 0x210000
	v_writelane_b32 v255, s4, 11
	s_mov_b32 s65, -1
	s_mov_b32 s57, 0x41000000
	v_mov_b32_e32 v196, 1.0
	v_mov_b32_e32 v197, 0xff800000
	v_mov_b32_e32 v98, 0x3f803f80
	v_mov_b32_e32 v198, 0xb0000
	s_branch .LBB0_261
.Lp0b_call:
	v_readlane_b32 s0, v255, 32
	v_readlane_b32 s1, v255, 33
	s_nop 4
	s_load_dwordx16 s[36:51], s[0:1], 0x0
	s_load_dwordx16 s[52:67], s[0:1], 0x40
	s_load_dwordx8 s[68:75], s[0:1], 0x80
	s_waitcnt lgkmcnt(0)
	s_branch .Lp0_entry

.LBB0_259:
	s_add_i32 s98, s98, 1
	s_bfe_u32 s100, s2, 0x10003
	s_add_i32 s100, s100, 1
	s_cmp_eq_u32 s98, s100
	s_cbranch_scc0 .Lp0b_no
	s_movk_i32 s98, 0x1000
	s_or_b32 s99, s99, 4
	s_branch .Lp0b_call

.LBB0_537:
	s_cmpk_ge_u32 s98, 0x1000
	s_cbranch_scc1 .Lp0b_ret_exit
	s_movk_i32 s98, 0x1000
	s_or_b32 s99, s99, 12
	s_branch .Lp0b_call
